# grid barriers 2-8 rewritten: per-XCC leader does the L2 writeback, single flat release counter polled by all workgroups, L1 invalidate issued before the poll
# speedup vs baseline: 1.0056x; 1.0050x over previous
; __device__ __forceinline__ unsigned xb_ld(unsigned* p)              { return __hip_atomic_load(p, __ATOMIC_RELAXED, __HIP_MEMORY_SCOPE_AGENT); }
; __device__ __forceinline__ unsigned xb_add(unsigned* p, unsigned v) { return __hip_atomic_fetch_add(p, v, __ATOMIC_RELAXED, __HIP_MEMORY_SCOPE_AGENT); }
; #define XB_SPIN(cond, bar) do { unsigned _sp = 0; while (cond) { __builtin_amdgcn_s_sleep(1); \
;     if ((++_sp & 255u) == 0u) { if (xb_ld(&(bar)[XB_TMO])) break; if (_sp > XB_SPIN_CAP) { atomicAdd(&(bar)[XB_TMO], 1u); break; } } } } while (0)
; __device__ __forceinline__ void xcd_barrier(const XcdBarrier& b) {
;     asm volatile("s_waitcnt vmcnt(0)" ::: "memory");
;     __syncthreads();
;     if (threadIdx.x == 0) {
;         unsigned* bar = b.bar;
;         __builtin_amdgcn_s_waitcnt(0);
;         unsigned nloc = b.st[0], nx = b.st[1];
;         if (nloc == 0u) { xcd_barrier_complete(bar, b.x, nloc, nx); b.st[0] = nloc; b.st[1] = nx; }
;         const unsigned old = xb_add(&bar[XB_XSUB(b.x)], 1u);
;         const unsigned gen = old / nloc;
;         if (old + 1u == (gen + 1u) * nloc) {
;             __builtin_amdgcn_fence(__ATOMIC_RELEASE, "agent");
;             asm volatile("s_waitcnt vmcnt(0)" ::: "memory");
;             const unsigned og = xb_add(&bar[XB_TOP], 1u);
;             const unsigned tg = og / nx;
;             if (og + 1u == (tg + 1u) * nx) xb_add(&bar[XB_TOPGEN], 1u);
;             else XB_SPIN(xb_ld(&bar[XB_TOPGEN]) == tg, bar);
;             __builtin_amdgcn_fence(__ATOMIC_ACQUIRE, "agent");
;             xb_add(&bar[XB_XGEN(b.x)], 1u);
;             asm volatile("s_waitcnt vmcnt(0)" ::: "memory");
;         } else {
;             XB_SPIN(xb_ld(&bar[XB_XGEN(b.x)]) == gen, bar);
;             __builtin_amdgcn_fence(__ATOMIC_ACQUIRE, "agent");
;             asm volatile("s_waitcnt vmcnt(0)" ::: "memory");
;         }
;     }
;     __syncthreads();
; }
.LBB0_175:
	s_waitcnt vmcnt(0) lgkmcnt(0)
	s_barrier
	v_readlane_b32 s74, v252, 15
	v_readlane_b32 s75, v252, 16
	v_readfirstlane_b32 s98, v222
	s_nop 3
	s_cmp_lg_u32 s98, 0
	s_cbranch_scc1 .Lsm2_done
	v_mov_b32_e32 v0, 0x23fc0
	ds_read_b64 v[2:3], v0
	v_readlane_b32 s99, v252, 3
	s_add_u32 s100, s58, 0x507000
	s_addc_u32 s101, s59, 0
	s_lshl_b32 s99, s99, 8
	v_mov_b32_e32 v0, s99
	v_mov_b32_e32 v1, 1
	s_mov_b64 exec, 1
	s_nop 1
	global_atomic_add v4, v0, v1, s[100:101] sc0
	s_waitcnt vmcnt(0) lgkmcnt(0)
	v_readfirstlane_b32 s99, v4
	v_readfirstlane_b32 vcc_lo, v2
	v_readfirstlane_b32 vcc_hi, v3
	s_add_u32 s100, s58, 0x500080
	s_addc_u32 s101, s59, 0
	v_mov_b32_e32 v0, 0
	s_add_u32 s99, s99, 1
	s_mul_i32 s98, vcc_lo, 1
	s_cmp_lg_u32 s99, s98
	s_cbranch_scc1 .Lsm2_nl
	buffer_wbl2 sc1
	s_waitcnt vmcnt(0)
	global_atomic_add v0, v1, s[100:101]
.Lsm2_nl:
	buffer_inv sc1
	s_mul_i32 s98, vcc_hi, 1
	s_mov_b32 s99, 0
.Lsm2_spin:
	global_load_dword v4, v0, s[100:101] sc1
	s_waitcnt vmcnt(0)
	v_readfirstlane_b32 vcc_lo, v4
	s_nop 0
	s_cmp_ge_u32 vcc_lo, s98
	s_cbranch_scc1 .Lsm2_rel
	s_sleep 1
	s_add_u32 s99, s99, 1
	s_cmp_lt_u32 s99, 0x40000
	s_cbranch_scc1 .Lsm2_spin
.Lsm2_rel:
	s_mov_b64 exec, -1
.Lsm2_done:
.LBB0_229:
	s_mov_b64 exec, -1
	s_cmpk_lt_i32 s2, 0x100
	s_cselect_b64 s[26:27], -1, 0
	v_mov_b32_e32 v15, v222
	s_waitcnt lgkmcnt(0)
	s_barrier
	s_and_b64 vcc, exec, s[26:27]
	v_readfirstlane_b32 s6, v15
	s_cbranch_vccz .LBB0_231
	s_lshr_b32 s4, s33, 29
	s_add_i32 s4, s2, s4
	s_ashr_i32 s5, s4, 3
	s_and_b32 s4, s4, -8
	s_sub_i32 s4, s2, s4
	s_lshl_b32 s8, s4, 5
	s_mul_i32 s7, s4, 33
	s_cmp_lt_i32 s4, 0
	s_cselect_b32 s4, s7, s8
	s_add_i32 s4, s4, s5
	s_ashr_i32 s5, s4, 31
	s_lshr_b32 s5, s5, 26
	s_add_i32 s5, s4, s5
	s_ashr_i32 s7, s5, 6
	s_and_b32 s5, s5, 0xffc0
	s_sub_i32 s4, s4, s5
	s_bfe_i32 s5, s4, 0x80000
	s_bfe_u32 s5, s5, 0x3000c
	s_add_i32 s5, s4, s5
	s_bfe_i32 s8, s5, 0x80000
	s_and_b32 s5, s5, 0xf8
	s_sub_i32 s4, s4, s5
	s_lshl_b32 s7, s7, 3
	s_sext_i32_i16 s8, s8
	s_sext_i32_i8 s4, s4
	s_add_i32 s13, s7, s4
	s_ashr_i32 s12, s8, 3

; __device__ __forceinline__ unsigned xb_ld(unsigned* p)              { return __hip_atomic_load(p, __ATOMIC_RELAXED, __HIP_MEMORY_SCOPE_AGENT); }
; __device__ __forceinline__ unsigned xb_add(unsigned* p, unsigned v) { return __hip_atomic_fetch_add(p, v, __ATOMIC_RELAXED, __HIP_MEMORY_SCOPE_AGENT); }
; #define XB_SPIN(cond, bar) do { unsigned _sp = 0; while (cond) { __builtin_amdgcn_s_sleep(1); \
;     if ((++_sp & 255u) == 0u) { if (xb_ld(&(bar)[XB_TMO])) break; if (_sp > XB_SPIN_CAP) { atomicAdd(&(bar)[XB_TMO], 1u); break; } } } } while (0)
; __device__ __forceinline__ void xcd_barrier(const XcdBarrier& b) {
;     asm volatile("s_waitcnt vmcnt(0)" ::: "memory");
;     __syncthreads();
;     if (threadIdx.x == 0) {
;         unsigned* bar = b.bar;
;         __builtin_amdgcn_s_waitcnt(0);
;         unsigned nloc = b.st[0], nx = b.st[1];
;         if (nloc == 0u) { xcd_barrier_complete(bar, b.x, nloc, nx); b.st[0] = nloc; b.st[1] = nx; }
;         const unsigned old = xb_add(&bar[XB_XSUB(b.x)], 1u);
;         const unsigned gen = old / nloc;
;         if (old + 1u == (gen + 1u) * nloc) {
;             __builtin_amdgcn_fence(__ATOMIC_RELEASE, "agent");
;             asm volatile("s_waitcnt vmcnt(0)" ::: "memory");
;             const unsigned og = xb_add(&bar[XB_TOP], 1u);
;             const unsigned tg = og / nx;
;             if (og + 1u == (tg + 1u) * nx) xb_add(&bar[XB_TOPGEN], 1u);
;             else XB_SPIN(xb_ld(&bar[XB_TOPGEN]) == tg, bar);
;             __builtin_amdgcn_fence(__ATOMIC_ACQUIRE, "agent");
;             xb_add(&bar[XB_XGEN(b.x)], 1u);
;             asm volatile("s_waitcnt vmcnt(0)" ::: "memory");
;         } else {
;             XB_SPIN(xb_ld(&bar[XB_XGEN(b.x)]) == gen, bar);
;             __builtin_amdgcn_fence(__ATOMIC_ACQUIRE, "agent");
;             asm volatile("s_waitcnt vmcnt(0)" ::: "memory");
;         }
;     }
;     __syncthreads();
; }
.LBB0_335:
	s_waitcnt vmcnt(0) lgkmcnt(0)
	s_barrier
	v_readfirstlane_b32 s98, v222
	s_nop 3
	s_cmp_lg_u32 s98, 0
	s_cbranch_scc1 .Lsm3_done
	v_mov_b32_e32 v0, 0x23fc0
	ds_read_b64 v[2:3], v0
	v_readlane_b32 s99, v252, 3
	s_add_u32 s100, s58, 0x507000
	s_addc_u32 s101, s59, 0
	s_lshl_b32 s99, s99, 8
	v_mov_b32_e32 v0, s99
	v_mov_b32_e32 v1, 1
	s_mov_b64 exec, 1
	s_nop 1
	global_atomic_add v4, v0, v1, s[100:101] sc0
	s_waitcnt vmcnt(0) lgkmcnt(0)
	v_readfirstlane_b32 s99, v4
	v_readfirstlane_b32 vcc_lo, v2
	v_readfirstlane_b32 vcc_hi, v3
	s_add_u32 s100, s58, 0x500080
	s_addc_u32 s101, s59, 0
	v_mov_b32_e32 v0, 0
	s_add_u32 s99, s99, 1
	s_mul_i32 s98, vcc_lo, 2
	s_cmp_lg_u32 s99, s98
	s_cbranch_scc1 .Lsm3_nl
	buffer_wbl2 sc1
	s_waitcnt vmcnt(0)
	global_atomic_add v0, v1, s[100:101]
.Lsm3_nl:
	buffer_inv sc1
	s_mul_i32 s98, vcc_hi, 2
	s_mov_b32 s99, 0

; __device__ __forceinline__ unsigned xb_ld(unsigned* p)              { return __hip_atomic_load(p, __ATOMIC_RELAXED, __HIP_MEMORY_SCOPE_AGENT); }
; __device__ __forceinline__ unsigned xb_add(unsigned* p, unsigned v) { return __hip_atomic_fetch_add(p, v, __ATOMIC_RELAXED, __HIP_MEMORY_SCOPE_AGENT); }
;     __host__ __device__ bool next(int i, Unit& u) const {
;         const long L = (long)i * G + c; if (L >= nwg) return false;
;         int wgid = (int)L; { const int q = nwg / NXCD, r = nwg % NXCD, xcd = wgid % NXCD, off = wgid / NXCD; wgid = (xcd < r ? xcd * (q + 1) : r * (q + 1) + (xcd - r) * q) + off; }
;         const int nig = WGM * nN, gid = wgid / nig, fm = gid * WGM, gsz = (nM - fm) < WGM ? (nM - fm) : WGM;
;         u.pm = fm + ((wgid % nig) % gsz); u.pn = (wgid % nig) / gsz; return true;
; __device__ __forceinline__ void xcd_barrier(const XcdBarrier& b) {
;     asm volatile("s_waitcnt vmcnt(0)" ::: "memory");
;     __syncthreads();
;     if (threadIdx.x == 0) {
;         unsigned* bar = b.bar;
;         __builtin_amdgcn_s_waitcnt(0);
;         unsigned nloc = b.st[0], nx = b.st[1];
;         if (nloc == 0u) { xcd_barrier_complete(bar, b.x, nloc, nx); b.st[0] = nloc; b.st[1] = nx; }
;         const unsigned old = xb_add(&bar[XB_XSUB(b.x)], 1u);
;         const unsigned gen = old / nloc;
;         if (old + 1u == (gen + 1u) * nloc) {
;             __builtin_amdgcn_fence(__ATOMIC_RELEASE, "agent");
;             asm volatile("s_waitcnt vmcnt(0)" ::: "memory");
;             const unsigned og = xb_add(&bar[XB_TOP], 1u);
;             const unsigned tg = og / nx;
;             if (og + 1u == (tg + 1u) * nx) xb_add(&bar[XB_TOPGEN], 1u);
;             else XB_SPIN(xb_ld(&bar[XB_TOPGEN]) == tg, bar);
;             __builtin_amdgcn_fence(__ATOMIC_ACQUIRE, "agent");
;             xb_add(&bar[XB_XGEN(b.x)], 1u);
;             asm volatile("s_waitcnt vmcnt(0)" ::: "memory");
;         } else {
;             XB_SPIN(xb_ld(&bar[XB_XGEN(b.x)]) == gen, bar);
;             __builtin_amdgcn_fence(__ATOMIC_ACQUIRE, "agent");
;             asm volatile("s_waitcnt vmcnt(0)" ::: "memory");
;         }
;     }
;     __syncthreads();
; }
.Lsm3_done:
.LBB0_388:
	s_mov_b64 exec, -1
	s_cmpk_lt_i32 s2, 0x400
	s_cselect_b64 s[6:7], -1, 0
	s_lshr_b32 s3, s33, 29
	s_add_i32 s3, s2, s3
	s_and_b32 s8, s3, -8
	s_sub_i32 s73, s2, s8
	s_ashr_i32 s3, s3, 3
	s_cmp_lt_i32 s73, 0
	v_writelane_b32 v252, s3, 28
	s_cselect_b64 s[8:9], -1, 0
	v_writelane_b32 v252, s8, 29
	v_mov_b32_e32 v14, v222
	s_waitcnt lgkmcnt(0)
	s_barrier
	v_writelane_b32 v252, s9, 30
	s_and_b64 vcc, exec, s[6:7]
	v_readfirstlane_b32 s9, v14
	s_cbranch_vccz .LBB0_390
	v_readlane_b32 s10, v252, 29
	s_lshl_b32 s8, s73, 7
	v_readlane_b32 s11, v252, 30
	s_mul_i32 s3, s73, 0x81
	s_and_b64 s[10:11], s[10:11], exec
	s_cselect_b32 s3, s3, s8
	v_readlane_b32 s8, v252, 28
	s_add_i32 s3, s3, s8
	s_ashr_i32 s8, s3, 31
	s_lshr_b32 s8, s8, 24
	s_add_i32 s8, s3, s8
	s_ashr_i32 s10, s8, 8
	s_and_b32 s8, s8, 0xffffff00
	s_sub_i32 s3, s3, s8
	s_sext_i32_i16 s8, s3
	s_bfe_u32 s8, s8, 0x3001c
	s_add_i32 s8, s3, s8
	s_sext_i32_i16 s11, s8
	s_and_b32 s8, s8, 0xfff8
	s_sub_i32 s3, s3, s8
	s_lshl_b32 s10, s10, 3
	s_sext_i32_i16 s3, s3
	s_add_i32 s46, s10, s3
	s_ashr_i32 s94, s11, 3

; __device__ __forceinline__ unsigned xb_ld(unsigned* p)              { return __hip_atomic_load(p, __ATOMIC_RELAXED, __HIP_MEMORY_SCOPE_AGENT); }
; __device__ __forceinline__ unsigned xb_add(unsigned* p, unsigned v) { return __hip_atomic_fetch_add(p, v, __ATOMIC_RELAXED, __HIP_MEMORY_SCOPE_AGENT); }
; #define XB_SPIN(cond, bar) do { unsigned _sp = 0; while (cond) { __builtin_amdgcn_s_sleep(1); \
;     if ((++_sp & 255u) == 0u) { if (xb_ld(&(bar)[XB_TMO])) break; if (_sp > XB_SPIN_CAP) { atomicAdd(&(bar)[XB_TMO], 1u); break; } } } } while (0)
; __device__ __forceinline__ void xcd_barrier(const XcdBarrier& b) {
;     asm volatile("s_waitcnt vmcnt(0)" ::: "memory");
;     __syncthreads();
;     if (threadIdx.x == 0) {
;         unsigned* bar = b.bar;
;         __builtin_amdgcn_s_waitcnt(0);
;         unsigned nloc = b.st[0], nx = b.st[1];
;         if (nloc == 0u) { xcd_barrier_complete(bar, b.x, nloc, nx); b.st[0] = nloc; b.st[1] = nx; }
;         const unsigned old = xb_add(&bar[XB_XSUB(b.x)], 1u);
;         const unsigned gen = old / nloc;
;         if (old + 1u == (gen + 1u) * nloc) {
;             __builtin_amdgcn_fence(__ATOMIC_RELEASE, "agent");
;             asm volatile("s_waitcnt vmcnt(0)" ::: "memory");
;             const unsigned og = xb_add(&bar[XB_TOP], 1u);
;             const unsigned tg = og / nx;
;             if (og + 1u == (tg + 1u) * nx) xb_add(&bar[XB_TOPGEN], 1u);
;             else XB_SPIN(xb_ld(&bar[XB_TOPGEN]) == tg, bar);
;             __builtin_amdgcn_fence(__ATOMIC_ACQUIRE, "agent");
;             xb_add(&bar[XB_XGEN(b.x)], 1u);
;             asm volatile("s_waitcnt vmcnt(0)" ::: "memory");
;         } else {
;             XB_SPIN(xb_ld(&bar[XB_XGEN(b.x)]) == gen, bar);
;             __builtin_amdgcn_fence(__ATOMIC_ACQUIRE, "agent");
;             asm volatile("s_waitcnt vmcnt(0)" ::: "memory");
;         }
;     }
;     __syncthreads();
; }
.LBB0_500:
	s_waitcnt vmcnt(0) lgkmcnt(0)
	s_barrier
	v_readfirstlane_b32 s98, v222
	s_nop 3
	s_cmp_lg_u32 s98, 0
	s_cbranch_scc1 .Lsm4_done
	v_mov_b32_e32 v0, 0x23fc0
	ds_read_b64 v[2:3], v0
	v_readlane_b32 s99, v252, 3
	s_add_u32 s100, s58, 0x507000
	s_addc_u32 s101, s59, 0
	s_lshl_b32 s99, s99, 8
	v_mov_b32_e32 v0, s99
	v_mov_b32_e32 v1, 1
	s_mov_b64 exec, 1
	s_nop 1
	global_atomic_add v4, v0, v1, s[100:101] sc0
	s_waitcnt vmcnt(0) lgkmcnt(0)
	v_readfirstlane_b32 s99, v4
	v_readfirstlane_b32 vcc_lo, v2
	v_readfirstlane_b32 vcc_hi, v3
	s_add_u32 s100, s58, 0x500080
	s_addc_u32 s101, s59, 0
	v_mov_b32_e32 v0, 0
	s_add_u32 s99, s99, 1
	s_mul_i32 s98, vcc_lo, 3
	s_cmp_lg_u32 s99, s98
	s_cbranch_scc1 .Lsm4_nl
	buffer_wbl2 sc1
	s_waitcnt vmcnt(0)
	global_atomic_add v0, v1, s[100:101]
.Lsm4_nl:
	buffer_inv sc1
	s_mul_i32 s98, vcc_hi, 3
	s_mov_b32 s99, 0

; #define LAS __attribute__((address_space(3)))
; __device__ __forceinline__ void xcd_barrier(const XcdBarrier& b) {
;     asm volatile("s_waitcnt vmcnt(0)" ::: "memory");
;     __syncthreads();
;     if (threadIdx.x == 0) {
;         unsigned* bar = b.bar;
;         __builtin_amdgcn_s_waitcnt(0);
;         unsigned nloc = b.st[0], nx = b.st[1];
;         if (nloc == 0u) { xcd_barrier_complete(bar, b.x, nloc, nx); b.st[0] = nloc; b.st[1] = nx; }
;         const unsigned old = xb_add(&bar[XB_XSUB(b.x)], 1u);
;         const unsigned gen = old / nloc;
;         if (old + 1u == (gen + 1u) * nloc) {
;             __builtin_amdgcn_fence(__ATOMIC_RELEASE, "agent");
;             asm volatile("s_waitcnt vmcnt(0)" ::: "memory");
;             const unsigned og = xb_add(&bar[XB_TOP], 1u);
;             const unsigned tg = og / nx;
;             if (og + 1u == (tg + 1u) * nx) xb_add(&bar[XB_TOPGEN], 1u);
;             else XB_SPIN(xb_ld(&bar[XB_TOPGEN]) == tg, bar);
;             __builtin_amdgcn_fence(__ATOMIC_ACQUIRE, "agent");
;             xb_add(&bar[XB_XGEN(b.x)], 1u);
;             asm volatile("s_waitcnt vmcnt(0)" ::: "memory");
;         } else {
;             XB_SPIN(xb_ld(&bar[XB_XGEN(b.x)]) == gen, bar);
;             __builtin_amdgcn_fence(__ATOMIC_ACQUIRE, "agent");
;             asm volatile("s_waitcnt vmcnt(0)" ::: "memory");
;         }
;     }
;     __syncthreads();
; }
; __global__ void __launch_bounds__(512, 2) mega_fwd(Args a) {
;     ...
;         float lam;
;         { int l_o = threadIdx.x; asm volatile("" : "+v"(l_o)); const int lane = l_o & 63; const float p1 = wave_sum(a.in[6][lane] * a.in[7][lane]), p2 = wave_sum(a.in[8][lane] * a.in[9][lane]); lam = __uint_as_float(__builtin_amdgcn_readfirstlane(__float_as_uint(expf(p1) - expf(p2) + 0.2f))); }
;         unsigned* cnt_u = (unsigned*)(a.ws + WS_BAR) + 3600; unsigned* cnt_c = (unsigned*)(a.ws + WS_BAR) + 3968;
;         volatile LAS unsigned* wq = (volatile LAS unsigned*)(lds + LDS_BYTES - 128);
;         const int xq = (int)(blockIdx.x & 7);
;     ...
; #pragma unroll 1
;         for (int ustat = blockIdx.x;; ustat += G) {
;             int ucode, useq;
;             if (ATT_DYNAMIC) {
;                 __syncthreads();
;                 if (threadIdx.x == 0) wq[0] = __hip_atomic_fetch_add(cnt_u + 16 * xq, 1u, __ATOMIC_RELAXED, __HIP_MEMORY_SCOPE_AGENT);
;                 __syncthreads();
.Lsm4_done:
.LBB0_553:
	s_mov_b64 exec, -1
	s_waitcnt lgkmcnt(0)
	v_mov_b32_e32 v0, v222
	s_barrier
	v_mbcnt_hi_u32_b32 v5, -1, v216
	v_and_b32_e32 v0, 63, v0
	v_lshlrev_b32_e32 v0, 2, v0
	global_load_dword v1, v0, s[48:49]
	global_load_dword v2, v0, s[50:51]
	global_load_dword v3, v0, s[16:17]
	global_load_dword v4, v0, s[18:19]
	v_and_b32_e32 v8, 64, v5
	v_xor_b32_e32 v9, 1, v5
	v_add_u32_e32 v8, 64, v8
	v_cmp_lt_i32_e32 vcc, v9, v8
	v_xor_b32_e32 v10, 2, v5
	v_xor_b32_e32 v11, 4, v5
	v_cndmask_b32_e32 v9, v5, v9, vcc
	v_lshlrev_b32_e32 v9, 2, v9
	v_cmp_lt_i32_e32 vcc, v10, v8
	v_xor_b32_e32 v12, 8, v5
	v_xor_b32_e32 v13, 16, v5
	v_cndmask_b32_e32 v10, v5, v10, vcc
	v_cmp_lt_i32_e32 vcc, v11, v8
	v_xor_b32_e32 v14, 32, v5
	s_mov_b32 s6, 0x3fb8aa3b
	v_cndmask_b32_e32 v11, v5, v11, vcc
	v_cmp_lt_i32_e32 vcc, v12, v8
	s_add_u32 s8, s58, 0xb200000
	s_addc_u32 s9, s59, 0
	v_cndmask_b32_e32 v12, v5, v12, vcc
	v_cmp_lt_i32_e32 vcc, v13, v8
	s_ashr_i32 s70, s2, 5
	s_mov_b32 s1, 0xc2ce8ed0
	v_cndmask_b32_e32 v13, v5, v13, vcc
	v_cmp_lt_i32_e32 vcc, v14, v8
	v_lshlrev_b32_e32 v8, 2, v10
	v_lshlrev_b32_e32 v10, 2, v11
	v_cndmask_b32_e32 v5, v5, v14, vcc
	v_lshlrev_b32_e32 v223, 2, v5
	v_lshlrev_b32_e32 v224, 2, v13
	s_cmp_eq_u32 s70, 7
	s_cselect_b32 s10, 3, 2
	s_cmp_gt_u32 s2, 31
	s_mov_b32 s0, 0x42b17218
	s_cselect_b64 s[12:13], -1, 0
	s_mov_b32 s11, 0
	v_mov_b32_e32 v6, 0x7f800000
	v_cndmask_b32_e64 v211, 0, 1, s[12:13]
	s_and_b64 s[12:13], s[12:13], exec
	s_movk_i32 s7, 0xce
	s_mov_b32 s3, s11
	s_cselect_b32 s71, s10, 1
	s_cmp_eq_u32 s70, 6
	s_cselect_b32 s80, s7, 0x89a
	s_lshl_b64 s[12:13], s[2:3], 17
	v_cvt_f32_ubyte0_e32 v212, s71
	s_add_u32 s3, s58, s12
	v_rcp_iflag_f32_e32 v213, v212
	v_mov_b32_e32 v7, 0x3e4ccccd
	s_addc_u32 s7, s59, s13
	s_mov_b32 s16, 2.0
	s_mov_b32 s18, 4.0
	s_mov_b32 s42, 0x40c00000
	s_add_u32 s44, s3, 0xc200000
	v_mov_b32_e32 v0, 0
	s_movk_i32 s23, 0x1000
	s_mov_b32 s50, 0x42fc0000
	s_movk_i32 s51, 0x110
	s_movk_i32 s68, 0x90
	s_mov_b32 s17, 0x40400000
	s_mov_b32 s19, 0x40a00000
	s_mov_b32 s43, 0x40e00000
	s_mov_b32 s69, 0x41000000
	v_mov_b32_e32 v210, 0x358637bd
	s_addc_u32 s45, s7, 0
	s_add_i32 s3, 0, 0x12000
	s_add_i32 s81, 0, 0x12800
	v_mov_b32_e32 v214, 0xff800000
	v_mov_b32_e32 v215, 0x42800000
	v_mov_b32_e32 v216, 0xfffff000
	v_mov_b32_e32 v217, 0x1000
	v_mov_b32_e32 v218, 0xf149f2ca
	s_mov_b32 s82, s2
	s_waitcnt vmcnt(2)
	v_mul_f32_e32 v15, v1, v2
	ds_bpermute_b32 v15, v9, v15
	s_waitcnt vmcnt(0)
	v_mul_f32_e32 v16, v3, v4
	ds_bpermute_b32 v9, v9, v16
	s_waitcnt lgkmcnt(1)
	v_fmac_f32_e32 v15, v1, v2
	ds_bpermute_b32 v1, v8, v15
	s_waitcnt lgkmcnt(1)
	v_fmac_f32_e32 v9, v3, v4
	ds_bpermute_b32 v2, v8, v9
	v_lshlrev_b32_e32 v3, 2, v12
	s_waitcnt lgkmcnt(1)
	v_add_f32_e32 v1, v15, v1
	ds_bpermute_b32 v4, v10, v1
	s_waitcnt lgkmcnt(1)
	v_add_f32_e32 v2, v9, v2
	ds_bpermute_b32 v5, v10, v2
	s_waitcnt lgkmcnt(1)
	v_add_f32_e32 v1, v1, v4
	ds_bpermute_b32 v4, v3, v1
	s_waitcnt lgkmcnt(1)
	v_add_f32_e32 v2, v2, v5
	ds_bpermute_b32 v3, v3, v2
	s_waitcnt lgkmcnt(1)
	v_add_f32_e32 v1, v1, v4
	s_waitcnt lgkmcnt(0)
	v_add_f32_e32 v2, v2, v3
	ds_bpermute_b32 v3, v224, v1
	ds_bpermute_b32 v4, v224, v2
	s_waitcnt lgkmcnt(1)
	v_add_f32_e32 v1, v1, v3
	s_waitcnt lgkmcnt(0)
	v_add_f32_e32 v2, v2, v4
	ds_bpermute_b32 v3, v223, v1
	ds_bpermute_b32 v4, v223, v2
	s_waitcnt lgkmcnt(1)
	v_add_f32_e32 v1, v1, v3
	s_waitcnt lgkmcnt(0)
	v_add_f32_e32 v2, v2, v4
	v_mul_f32_e32 v3, 0x3fb8aa3b, v1
	v_mul_f32_e32 v4, 0x3fb8aa3b, v2
	v_fma_f32 v5, v1, s6, -v3
	v_rndne_f32_e32 v8, v3
	v_fma_f32 v9, v2, s6, -v4
	v_rndne_f32_e32 v10, v4
	v_fmac_f32_e32 v5, 0x32a5705f, v1
	v_sub_f32_e32 v3, v3, v8
	v_fmac_f32_e32 v9, 0x32a5705f, v2
	v_sub_f32_e32 v4, v4, v10
	v_add_f32_e32 v3, v3, v5
	v_cvt_i32_f32_e32 v8, v8
	v_add_f32_e32 v4, v4, v9
	v_exp_f32_e32 v3, v3
	v_cvt_i32_f32_e32 v10, v10
	v_exp_f32_e32 v4, v4
	v_cmp_ngt_f32_e32 vcc, s1, v1
	v_ldexp_f32 v3, v3, v8
	v_ldexp_f32 v4, v4, v10
	v_cndmask_b32_e32 v3, 0, v3, vcc
	v_cmp_ngt_f32_e32 vcc, s1, v2
	s_nop 1
	v_cndmask_b32_e32 v4, 0, v4, vcc
	v_cmp_nlt_f32_e32 vcc, s0, v1
	s_nop 1
	v_cndmask_b32_e32 v1, v6, v3, vcc
	v_cmp_nlt_f32_e32 vcc, s0, v2
	s_nop 1
	v_cndmask_b32_e32 v2, v6, v4, vcc
	v_sub_f32_e32 v1, v1, v2
	s_nop 0
	v_readfirstlane_b32 s0, v1
	s_nop 1
	v_add_f32_e32 v148, s0, v7
	v_mov_b32_e32 v149, v148
	s_branch .LBB0_557

; __device__ __forceinline__ unsigned xb_ld(unsigned* p)              { return __hip_atomic_load(p, __ATOMIC_RELAXED, __HIP_MEMORY_SCOPE_AGENT); }
; __device__ __forceinline__ unsigned xb_add(unsigned* p, unsigned v) { return __hip_atomic_fetch_add(p, v, __ATOMIC_RELAXED, __HIP_MEMORY_SCOPE_AGENT); }
; #define XB_SPIN(cond, bar) do { unsigned _sp = 0; while (cond) { __builtin_amdgcn_s_sleep(1); \
;     if ((++_sp & 255u) == 0u) { if (xb_ld(&(bar)[XB_TMO])) break; if (_sp > XB_SPIN_CAP) { atomicAdd(&(bar)[XB_TMO], 1u); break; } } } } while (0)
; __device__ __forceinline__ void xcd_barrier(const XcdBarrier& b) {
;     asm volatile("s_waitcnt vmcnt(0)" ::: "memory");
;     __syncthreads();
;     if (threadIdx.x == 0) {
;         unsigned* bar = b.bar;
;         __builtin_amdgcn_s_waitcnt(0);
;         unsigned nloc = b.st[0], nx = b.st[1];
;         if (nloc == 0u) { xcd_barrier_complete(bar, b.x, nloc, nx); b.st[0] = nloc; b.st[1] = nx; }
;         const unsigned old = xb_add(&bar[XB_XSUB(b.x)], 1u);
;         const unsigned gen = old / nloc;
;         if (old + 1u == (gen + 1u) * nloc) {
;             __builtin_amdgcn_fence(__ATOMIC_RELEASE, "agent");
;             asm volatile("s_waitcnt vmcnt(0)" ::: "memory");
;             const unsigned og = xb_add(&bar[XB_TOP], 1u);
;             const unsigned tg = og / nx;
;             if (og + 1u == (tg + 1u) * nx) xb_add(&bar[XB_TOPGEN], 1u);
;             else XB_SPIN(xb_ld(&bar[XB_TOPGEN]) == tg, bar);
;             __builtin_amdgcn_fence(__ATOMIC_ACQUIRE, "agent");
;             xb_add(&bar[XB_XGEN(b.x)], 1u);
;             asm volatile("s_waitcnt vmcnt(0)" ::: "memory");
;         } else {
;             XB_SPIN(xb_ld(&bar[XB_XGEN(b.x)]) == gen, bar);
;             __builtin_amdgcn_fence(__ATOMIC_ACQUIRE, "agent");
;             asm volatile("s_waitcnt vmcnt(0)" ::: "memory");
;         }
;     }
;     __syncthreads();
; }
.LBB0_715:
	s_waitcnt vmcnt(0) lgkmcnt(0)
	s_barrier
	v_readfirstlane_b32 s98, v222
	s_nop 3
	s_cmp_lg_u32 s98, 0
	s_cbranch_scc1 .Lsm5_done
	v_mov_b32_e32 v0, 0x23fc0
	ds_read_b64 v[2:3], v0
	v_readlane_b32 s99, v252, 3
	s_add_u32 s100, s58, 0x507000
	s_addc_u32 s101, s59, 0
	s_lshl_b32 s99, s99, 8
	v_mov_b32_e32 v0, s99
	v_mov_b32_e32 v1, 1
	s_mov_b64 exec, 1
	s_nop 1
	global_atomic_add v4, v0, v1, s[100:101] sc0
	s_waitcnt vmcnt(0) lgkmcnt(0)
	v_readfirstlane_b32 s99, v4
	v_readfirstlane_b32 vcc_lo, v2
	v_readfirstlane_b32 vcc_hi, v3
	s_add_u32 s100, s58, 0x500080
	s_addc_u32 s101, s59, 0
	v_mov_b32_e32 v0, 0
	s_add_u32 s99, s99, 1
	s_mul_i32 s98, vcc_lo, 4
	s_cmp_lg_u32 s99, s98
	s_cbranch_scc1 .Lsm5_nl
	buffer_wbl2 sc1
	s_waitcnt vmcnt(0)
	global_atomic_add v0, v1, s[100:101]
.Lsm5_nl:
	buffer_inv sc1
	s_mul_i32 s98, vcc_hi, 4
	s_mov_b32 s99, 0

; template <class Epi, class Sched, bool ALIGN_EPI = false, bool SP2 = false>
; __device__ __forceinline__ void gemm_phase(PG8_LAS unsigned char* lds, const Gemm g, const Sched& S, const Epi& E) {
;     int tid_o = threadIdx.x; asm volatile("" : "+v"(tid_o));
;     const int tid = tid_o, wid = __builtin_amdgcn_readfirstlane(tid >> 6), lane = tid & 63, wr = wid >> 2, wc = wid & 3, fr = lane & 15, fq = lane >> 4;
;     const int K = g.K, nt = K / BK;
;     unsigned voffA[2], voffB[2];
; #pragma unroll
;     for (int i = 0; i < 2; ++i) { int R, C; stage_rc(tid * 16 + i * 8192, R, C); const int Rb = Epi::PERM ? ((R & ~31) + perm32(R & 31)) : R;
;         voffA[i] = (unsigned)(R * K + C) * 2u; voffB[i] = (unsigned)(Rb * K + C) * 2u; }
;     const size_t kstep = (size_t)(BK * 2);
;     const size_t hstep = (size_t)HALF * K * 2;
;     const size_t tstep = 2 * hstep;
;     const unsigned ldsw = (unsigned)wid * 1024u;
;     const int aoff = lds_byte(wr * 64 + fr, fq * 8), boff = lds_byte(wc * 32 + fr, fq * 8);
; __device__ __forceinline__ void xcd_barrier(const XcdBarrier& b) {
;     asm volatile("s_waitcnt vmcnt(0)" ::: "memory");
;     __syncthreads();
;     if (threadIdx.x == 0) {
;         unsigned* bar = b.bar;
;         __builtin_amdgcn_s_waitcnt(0);
;         unsigned nloc = b.st[0], nx = b.st[1];
;         if (nloc == 0u) { xcd_barrier_complete(bar, b.x, nloc, nx); b.st[0] = nloc; b.st[1] = nx; }
;         const unsigned old = xb_add(&bar[XB_XSUB(b.x)], 1u);
;         const unsigned gen = old / nloc;
;         if (old + 1u == (gen + 1u) * nloc) {
;             __builtin_amdgcn_fence(__ATOMIC_RELEASE, "agent");
;             asm volatile("s_waitcnt vmcnt(0)" ::: "memory");
;             const unsigned og = xb_add(&bar[XB_TOP], 1u);
;             const unsigned tg = og / nx;
;             if (og + 1u == (tg + 1u) * nx) xb_add(&bar[XB_TOPGEN], 1u);
;             else XB_SPIN(xb_ld(&bar[XB_TOPGEN]) == tg, bar);
;             __builtin_amdgcn_fence(__ATOMIC_ACQUIRE, "agent");
;             xb_add(&bar[XB_XGEN(b.x)], 1u);
;             asm volatile("s_waitcnt vmcnt(0)" ::: "memory");
;         } else {
;             XB_SPIN(xb_ld(&bar[XB_XGEN(b.x)]) == gen, bar);
;             __builtin_amdgcn_fence(__ATOMIC_ACQUIRE, "agent");
;             asm volatile("s_waitcnt vmcnt(0)" ::: "memory");
;         }
;     }
;     __syncthreads();
; }
.Lsm5_done:
.LBB0_768:
	s_mov_b64 exec, -1
	v_mov_b32_e32 v9, v222
	s_waitcnt lgkmcnt(0)
	s_barrier
	s_and_b64 vcc, exec, s[26:27]
	v_readfirstlane_b32 s7, v9
	s_cbranch_vccz .LBB0_788
	v_lshlrev_b32_e32 v0, 4, v9
	v_add_u32_e32 v1, 0x2000, v0
	v_ashrrev_i32_e32 v2, 31, v1
	v_lshrrev_b32_e32 v2, 22, v2
	v_add_u32_e32 v2, v1, v2
	v_ashrrev_i32_e32 v8, 10, v2
	v_mul_i32_i24_e32 v2, 0x400, v8
	v_sub_u32_e32 v1, v1, v2
	v_lshrrev_b32_e32 v2, 4, v1
	v_bitop3_b32 v1, v2, v1, 32 bitop3:0x6c
	v_ashrrev_i32_e32 v2, 31, v1
	v_lshrrev_b32_e32 v2, 26, v2
	v_add_u32_e32 v2, v1, v2
	v_lshlrev_b32_e32 v3, 3, v8
	v_ashrrev_i32_e32 v10, 6, v2
	v_and_b32_e32 v3, -16, v3
	v_add_u32_e32 v3, v10, v3
	v_and_b32_e32 v4, 3, v10
	s_mov_b32 s0, 0x1fffe0
	v_lshrrev_b32_e32 v5, 2, v3
	v_lshlrev_b32_e32 v6, 1, v3
	v_and_b32_e32 v2, 0xc0, v2
	v_and_or_b32 v4, v3, s0, v4
	v_and_b32_e32 v5, 4, v5
	v_and_b32_e32 v6, 24, v6
	v_sub_u32_e32 v1, v1, v2
	v_mov_b32_e32 v2, 1
	v_or3_b32 v4, v4, v5, v6
	v_lshlrev_b32_e32 v5, 5, v8
	v_ashrrev_i16_sdwa v1, v2, sext(v1) dst_sel:DWORD dst_unused:UNUSED_PAD src0_sel:DWORD src1_sel:BYTE_0
	v_and_b32_e32 v5, 32, v5
	v_bfe_i32 v11, v1, 0, 16
	v_add_lshl_u32 v1, v5, v11, 1
	v_lshl_add_u32 v128, v4, 11, v1
	v_lshl_add_u32 v130, v3, 11, v1
	v_bfe_i32 v1, v9, 27, 1
	v_lshrrev_b32_e32 v1, 22, v1
	v_add_u32_e32 v1, v0, v1
	v_and_b32_e32 v1, 0xfffffc00, v1
	v_sub_u32_e32 v0, v0, v1
	v_lshrrev_b32_e32 v1, 4, v0
	v_ashrrev_i32_e32 v3, 31, v9
	v_bitop3_b32 v0, v1, v0, 32 bitop3:0x6c
	v_lshrrev_b32_e32 v3, 26, v3
	v_ashrrev_i32_e32 v1, 31, v0
	v_add_u32_e32 v3, v9, v3
	v_lshrrev_b32_e32 v1, 26, v1
	v_ashrrev_i32_e32 v13, 6, v3
	v_add_u32_e32 v1, v0, v1
	v_lshlrev_b32_e32 v3, 3, v13
	v_ashrrev_i32_e32 v12, 6, v1
	v_and_b32_e32 v3, -16, v3
	v_add_u32_e32 v3, v12, v3
	v_and_b32_e32 v4, 3, v12
	s_ashr_i32 s13, s7, 6
	v_and_or_b32 v4, v3, s0, v4
	v_readlane_b32 s0, v252, 29
	s_ashr_i32 s12, s7, 8
	s_lshl_b32 s3, s13, 10
	v_readlane_b32 s1, v252, 30
	s_and_b64 s[0:1], s[0:1], exec
	v_readlane_b32 s0, v252, 31
	s_mul_i32 s1, s73, 33
	s_cselect_b32 s0, s1, s0
	v_readlane_b32 s1, v252, 28
	s_add_i32 s0, s0, s1
	s_ashr_i32 s1, s0, 31
	s_lshr_b32 s1, s1, 26
	s_add_i32 s1, s0, s1
	s_ashr_i32 s6, s1, 6
	s_andn2_b32 s1, s1, 63
	s_sub_i32 s0, s0, s1
	s_bfe_i32 s1, s0, 0x80000
	s_bfe_u32 s1, s1, 0x3000c
	s_add_i32 s1, s0, s1
	s_lshl_b32 s10, s6, 3
	s_bfe_i32 s6, s1, 0x80000
	s_and_b32 s1, s1, 0xf8
	s_sub_i32 s0, s0, s1
	s_sext_i32_i16 s6, s6
	s_sext_i32_i8 s0, s0
	v_lshrrev_b32_e32 v5, 2, v3
	v_lshlrev_b32_e32 v6, 1, v3
	v_and_b32_e32 v1, 0xc0, v1
	s_lshr_b32 s6, s6, 3
	s_add_i32 s44, s10, s0
	v_and_b32_e32 v5, 4, v5
	v_and_b32_e32 v6, 24, v6
	v_sub_u32_e32 v0, v0, v1
	s_ashr_i32 s45, s44, 31
	s_bfe_i64 s[10:11], s[6:7], 0x100000
	v_or3_b32 v4, v4, v5, v6
	v_lshlrev_b32_e32 v5, 5, v13
	v_ashrrev_i16_sdwa v0, v2, sext(v0) dst_sel:DWORD dst_unused:UNUSED_PAD src0_sel:DWORD src1_sel:BYTE_0
	s_lshl_b64 s[0:1], s[44:45], 19
	s_lshl_b64 s[10:11], s[10:11], 19
	v_readlane_b32 s14, v252, 4
	v_and_b32_e32 v5, 32, v5
	v_bfe_i32 v14, v0, 0, 16
	v_readlane_b32 s15, v252, 5
	s_add_u32 s48, s14, s10
	v_add_lshl_u32 v0, v5, v14, 1
	s_addc_u32 s49, s15, s11
	s_add_i32 s14, s3, 0
	v_lshl_add_u32 v132, v4, 11, v0
	s_add_i32 m0, s14, 0x10000
	v_lshl_add_u32 v134, v3, 11, v0
	global_load_lds_dwordx4 v132, s[48:49]
	s_add_i32 m0, s14, 0x12000
	s_add_u32 s10, s48, 0x40000
	global_load_lds_dwordx4 v128, s[48:49]
	s_addc_u32 s11, s49, 0
	s_add_i32 m0, s14, 0x14000
	v_mov_b32_e32 v133, 0
	global_load_lds_dwordx4 v132, s[10:11]
	s_add_i32 m0, s14, 0x16000
	s_add_u32 s46, s38, s0
	s_addc_u32 s47, s39, s1
	s_add_i32 s15, s14, 0x2000
	global_load_lds_dwordx4 v128, s[10:11]
	s_mov_b32 m0, s14
	s_add_u32 s0, s46, 0x40000
	global_load_lds_dwordx4 v134, s[46:47]
	s_mov_b32 m0, s15
	s_addc_u32 s1, s47, 0
	s_add_i32 s22, s14, 0x4000
	global_load_lds_dwordx4 v130, s[46:47]
	s_mov_b32 m0, s22
	s_add_i32 s23, s14, 0x6000
	global_load_lds_dwordx4 v134, s[0:1]
	s_mov_b32 m0, s23
	v_mov_b32_e32 v129, v133
	global_load_lds_dwordx4 v130, s[0:1]
	v_mov_b32_e32 v135, v133
	v_mov_b32_e32 v131, v133
	s_cmp_eq_u32 s12, 1
	s_mov_b32 s34, 0
	v_lshl_add_u64 v[6:7], s[48:49], 0, v[132:133]
	v_lshl_add_u64 v[4:5], s[48:49], 0, v[128:129]
	v_lshl_add_u64 v[0:1], s[46:47], 0, v[134:135]
	s_cselect_b64 s[0:1], -1, 0
	s_cmp_lg_u32 s12, 1
	v_lshl_add_u64 v[2:3], s[46:47], 0, v[130:131]
	s_cbranch_scc1 .LBB0_771
	s_barrier

; __device__ __forceinline__ unsigned xb_ld(unsigned* p)              { return __hip_atomic_load(p, __ATOMIC_RELAXED, __HIP_MEMORY_SCOPE_AGENT); }
; __device__ __forceinline__ unsigned xb_add(unsigned* p, unsigned v) { return __hip_atomic_fetch_add(p, v, __ATOMIC_RELAXED, __HIP_MEMORY_SCOPE_AGENT); }
; #define XB_SPIN(cond, bar) do { unsigned _sp = 0; while (cond) { __builtin_amdgcn_s_sleep(1); \
;     if ((++_sp & 255u) == 0u) { if (xb_ld(&(bar)[XB_TMO])) break; if (_sp > XB_SPIN_CAP) { atomicAdd(&(bar)[XB_TMO], 1u); break; } } } } while (0)
; __device__ __forceinline__ void xcd_barrier(const XcdBarrier& b) {
;     asm volatile("s_waitcnt vmcnt(0)" ::: "memory");
;     __syncthreads();
;     if (threadIdx.x == 0) {
;         unsigned* bar = b.bar;
;         __builtin_amdgcn_s_waitcnt(0);
;         unsigned nloc = b.st[0], nx = b.st[1];
;         if (nloc == 0u) { xcd_barrier_complete(bar, b.x, nloc, nx); b.st[0] = nloc; b.st[1] = nx; }
;         const unsigned old = xb_add(&bar[XB_XSUB(b.x)], 1u);
;         const unsigned gen = old / nloc;
;         if (old + 1u == (gen + 1u) * nloc) {
;             __builtin_amdgcn_fence(__ATOMIC_RELEASE, "agent");
;             asm volatile("s_waitcnt vmcnt(0)" ::: "memory");
;             const unsigned og = xb_add(&bar[XB_TOP], 1u);
;             const unsigned tg = og / nx;
;             if (og + 1u == (tg + 1u) * nx) xb_add(&bar[XB_TOPGEN], 1u);
;             else XB_SPIN(xb_ld(&bar[XB_TOPGEN]) == tg, bar);
;             __builtin_amdgcn_fence(__ATOMIC_ACQUIRE, "agent");
;             xb_add(&bar[XB_XGEN(b.x)], 1u);
;             asm volatile("s_waitcnt vmcnt(0)" ::: "memory");
;         } else {
;             XB_SPIN(xb_ld(&bar[XB_XGEN(b.x)]) == gen, bar);
;             __builtin_amdgcn_fence(__ATOMIC_ACQUIRE, "agent");
;             asm volatile("s_waitcnt vmcnt(0)" ::: "memory");
;         }
;     }
;     __syncthreads();
; }
.LBB0_808:
	s_waitcnt vmcnt(0) lgkmcnt(0)
	s_barrier
	v_readfirstlane_b32 s98, v222
	s_nop 3
	s_cmp_lg_u32 s98, 0
	s_cbranch_scc1 .Lsm6_done
	v_mov_b32_e32 v0, 0x23fc0
	ds_read_b64 v[2:3], v0
	v_readlane_b32 s99, v252, 3
	s_add_u32 s100, s58, 0x507000
	s_addc_u32 s101, s59, 0
	s_lshl_b32 s99, s99, 8
	v_mov_b32_e32 v0, s99
	v_mov_b32_e32 v1, 1
	s_mov_b64 exec, 1
	s_nop 1
	global_atomic_add v4, v0, v1, s[100:101] sc0
	s_waitcnt vmcnt(0) lgkmcnt(0)
	v_readfirstlane_b32 s99, v4
	v_readfirstlane_b32 vcc_lo, v2
	v_readfirstlane_b32 vcc_hi, v3
	s_add_u32 s100, s58, 0x500080
	s_addc_u32 s101, s59, 0
	v_mov_b32_e32 v0, 0
	s_add_u32 s99, s99, 1
	s_mul_i32 s98, vcc_lo, 5
	s_cmp_lg_u32 s99, s98
	s_cbranch_scc1 .Lsm6_nl
	buffer_wbl2 sc1
	s_waitcnt vmcnt(0)
	global_atomic_add v0, v1, s[100:101]
.Lsm6_nl:
	buffer_inv sc1
	s_mul_i32 s98, vcc_hi, 5
	s_mov_b32 s99, 0

; __device__ __forceinline__ unsigned xb_ld(unsigned* p)              { return __hip_atomic_load(p, __ATOMIC_RELAXED, __HIP_MEMORY_SCOPE_AGENT); }
; __device__ __forceinline__ unsigned xb_add(unsigned* p, unsigned v) { return __hip_atomic_fetch_add(p, v, __ATOMIC_RELAXED, __HIP_MEMORY_SCOPE_AGENT); }
;     __host__ __device__ bool next(int i, Unit& u) const {
;         const long L = (long)i * G + c; if (L >= nwg) return false;
;         int wgid = (int)L; { const int q = nwg / NXCD, r = nwg % NXCD, xcd = wgid % NXCD, off = wgid / NXCD; wgid = (xcd < r ? xcd * (q + 1) : r * (q + 1) + (xcd - r) * q) + off; }
;         const int nig = WGM * nN, gid = wgid / nig, fm = gid * WGM, gsz = (nM - fm) < WGM ? (nM - fm) : WGM;
;         u.pm = fm + ((wgid % nig) % gsz); u.pn = (wgid % nig) / gsz; return true;
; __device__ __forceinline__ void xcd_barrier(const XcdBarrier& b) {
;     asm volatile("s_waitcnt vmcnt(0)" ::: "memory");
;     __syncthreads();
;     if (threadIdx.x == 0) {
;         unsigned* bar = b.bar;
;         __builtin_amdgcn_s_waitcnt(0);
;         unsigned nloc = b.st[0], nx = b.st[1];
;         if (nloc == 0u) { xcd_barrier_complete(bar, b.x, nloc, nx); b.st[0] = nloc; b.st[1] = nx; }
;         const unsigned old = xb_add(&bar[XB_XSUB(b.x)], 1u);
;         const unsigned gen = old / nloc;
;         if (old + 1u == (gen + 1u) * nloc) {
;             __builtin_amdgcn_fence(__ATOMIC_RELEASE, "agent");
;             asm volatile("s_waitcnt vmcnt(0)" ::: "memory");
;             const unsigned og = xb_add(&bar[XB_TOP], 1u);
;             const unsigned tg = og / nx;
;             if (og + 1u == (tg + 1u) * nx) xb_add(&bar[XB_TOPGEN], 1u);
;             else XB_SPIN(xb_ld(&bar[XB_TOPGEN]) == tg, bar);
;             __builtin_amdgcn_fence(__ATOMIC_ACQUIRE, "agent");
;             xb_add(&bar[XB_XGEN(b.x)], 1u);
;             asm volatile("s_waitcnt vmcnt(0)" ::: "memory");
;         } else {
;             XB_SPIN(xb_ld(&bar[XB_XGEN(b.x)]) == gen, bar);
;             __builtin_amdgcn_fence(__ATOMIC_ACQUIRE, "agent");
;             asm volatile("s_waitcnt vmcnt(0)" ::: "memory");
;         }
;     }
;     __syncthreads();
; }
.Lsm6_done:
.LBB0_861:
	s_mov_b64 exec, -1
	v_mov_b32_e32 v8, v222
	s_waitcnt lgkmcnt(0)
	s_barrier
	s_and_b64 vcc, exec, s[26:27]
	v_readfirstlane_b32 s6, v8
	s_cbranch_vccz .LBB0_863
	v_readlane_b32 s0, v252, 29
	v_readlane_b32 s1, v252, 30
	s_and_b64 s[0:1], s[0:1], exec
	v_readlane_b32 s0, v252, 31
	s_mul_i32 s1, s73, 33
	s_cselect_b32 s0, s1, s0
	v_readlane_b32 s1, v252, 28
	s_add_i32 s0, s0, s1
	s_ashr_i32 s1, s0, 31
	s_lshr_b32 s1, s1, 26
	s_add_i32 s1, s0, s1
	s_ashr_i32 s3, s1, 6
	s_andn2_b32 s1, s1, 63
	s_sub_i32 s0, s0, s1
	s_bfe_i32 s1, s0, 0x80000
	s_bfe_u32 s1, s1, 0x3000c
	s_add_i32 s1, s0, s1
	s_bfe_i32 s7, s1, 0x80000
	s_and_b32 s1, s1, 0xf8
	s_sub_i32 s0, s0, s1
	s_lshl_b32 s3, s3, 3
	s_sext_i32_i16 s7, s7
	s_sext_i32_i8 s0, s0
	s_add_i32 s10, s3, s0
	s_ashr_i32 s16, s7, 3

; __device__ __forceinline__ unsigned xb_ld(unsigned* p)              { return __hip_atomic_load(p, __ATOMIC_RELAXED, __HIP_MEMORY_SCOPE_AGENT); }
; __device__ __forceinline__ unsigned xb_add(unsigned* p, unsigned v) { return __hip_atomic_fetch_add(p, v, __ATOMIC_RELAXED, __HIP_MEMORY_SCOPE_AGENT); }
; #define XB_SPIN(cond, bar) do { unsigned _sp = 0; while (cond) { __builtin_amdgcn_s_sleep(1); \
;     if ((++_sp & 255u) == 0u) { if (xb_ld(&(bar)[XB_TMO])) break; if (_sp > XB_SPIN_CAP) { atomicAdd(&(bar)[XB_TMO], 1u); break; } } } } while (0)
; __device__ __forceinline__ void xcd_barrier(const XcdBarrier& b) {
;     asm volatile("s_waitcnt vmcnt(0)" ::: "memory");
;     __syncthreads();
;     if (threadIdx.x == 0) {
;         unsigned* bar = b.bar;
;         __builtin_amdgcn_s_waitcnt(0);
;         unsigned nloc = b.st[0], nx = b.st[1];
;         if (nloc == 0u) { xcd_barrier_complete(bar, b.x, nloc, nx); b.st[0] = nloc; b.st[1] = nx; }
;         const unsigned old = xb_add(&bar[XB_XSUB(b.x)], 1u);
;         const unsigned gen = old / nloc;
;         if (old + 1u == (gen + 1u) * nloc) {
;             __builtin_amdgcn_fence(__ATOMIC_RELEASE, "agent");
;             asm volatile("s_waitcnt vmcnt(0)" ::: "memory");
;             const unsigned og = xb_add(&bar[XB_TOP], 1u);
;             const unsigned tg = og / nx;
;             if (og + 1u == (tg + 1u) * nx) xb_add(&bar[XB_TOPGEN], 1u);
;             else XB_SPIN(xb_ld(&bar[XB_TOPGEN]) == tg, bar);
;             __builtin_amdgcn_fence(__ATOMIC_ACQUIRE, "agent");
;             xb_add(&bar[XB_XGEN(b.x)], 1u);
;             asm volatile("s_waitcnt vmcnt(0)" ::: "memory");
;         } else {
;             XB_SPIN(xb_ld(&bar[XB_XGEN(b.x)]) == gen, bar);
;             __builtin_amdgcn_fence(__ATOMIC_ACQUIRE, "agent");
;             asm volatile("s_waitcnt vmcnt(0)" ::: "memory");
;         }
;     }
;     __syncthreads();
; }
.LBB0_963:
	s_waitcnt vmcnt(0) lgkmcnt(0)
	s_barrier
	v_readfirstlane_b32 s98, v222
	s_nop 3
	s_cmp_lg_u32 s98, 0
	s_cbranch_scc1 .Lsm7_done
	v_mov_b32_e32 v0, 0x23fc0
	ds_read_b64 v[2:3], v0
	v_readlane_b32 s99, v252, 3
	s_add_u32 s100, s58, 0x507000
	s_addc_u32 s101, s59, 0
	s_lshl_b32 s99, s99, 8
	v_mov_b32_e32 v0, s99
	v_mov_b32_e32 v1, 1
	s_mov_b64 exec, 1
	s_nop 1
	global_atomic_add v4, v0, v1, s[100:101] sc0
	s_waitcnt vmcnt(0) lgkmcnt(0)
	v_readfirstlane_b32 s99, v4
	v_readfirstlane_b32 vcc_lo, v2
	v_readfirstlane_b32 vcc_hi, v3
	s_add_u32 s100, s58, 0x500080
	s_addc_u32 s101, s59, 0
	v_mov_b32_e32 v0, 0
	s_add_u32 s99, s99, 1
	s_mul_i32 s98, vcc_lo, 6
	s_cmp_lg_u32 s99, s98
	s_cbranch_scc1 .Lsm7_nl
	buffer_wbl2 sc1
	s_waitcnt vmcnt(0)
	global_atomic_add v0, v1, s[100:101]
.Lsm7_nl:
	buffer_inv sc1
	s_mul_i32 s98, vcc_hi, 6
	s_mov_b32 s99, 0

; template <class Epi, class Sched, bool ALIGN_EPI = false, bool SP2 = false>
; __device__ __forceinline__ void gemm_phase(PG8_LAS unsigned char* lds, const Gemm g, const Sched& S, const Epi& E) {
;     int tid_o = threadIdx.x; asm volatile("" : "+v"(tid_o));
;     const int tid = tid_o, wid = __builtin_amdgcn_readfirstlane(tid >> 6), lane = tid & 63, wr = wid >> 2, wc = wid & 3, fr = lane & 15, fq = lane >> 4;
;     const int K = g.K, nt = K / BK;
;     unsigned voffA[2], voffB[2];
; #pragma unroll
;     for (int i = 0; i < 2; ++i) { int R, C; stage_rc(tid * 16 + i * 8192, R, C); const int Rb = Epi::PERM ? ((R & ~31) + perm32(R & 31)) : R;
;         voffA[i] = (unsigned)(R * K + C) * 2u; voffB[i] = (unsigned)(Rb * K + C) * 2u; }
;     const size_t kstep = (size_t)(BK * 2);
;     const size_t hstep = (size_t)HALF * K * 2;
;     const size_t tstep = 2 * hstep;
;     const unsigned ldsw = (unsigned)wid * 1024u;
;     const int aoff = lds_byte(wr * 64 + fr, fq * 8), boff = lds_byte(wc * 32 + fr, fq * 8);
; __device__ __forceinline__ void xcd_barrier(const XcdBarrier& b) {
;     asm volatile("s_waitcnt vmcnt(0)" ::: "memory");
;     __syncthreads();
;     if (threadIdx.x == 0) {
;         unsigned* bar = b.bar;
;         __builtin_amdgcn_s_waitcnt(0);
;         unsigned nloc = b.st[0], nx = b.st[1];
;         if (nloc == 0u) { xcd_barrier_complete(bar, b.x, nloc, nx); b.st[0] = nloc; b.st[1] = nx; }
;         const unsigned old = xb_add(&bar[XB_XSUB(b.x)], 1u);
;         const unsigned gen = old / nloc;
;         if (old + 1u == (gen + 1u) * nloc) {
;             __builtin_amdgcn_fence(__ATOMIC_RELEASE, "agent");
;             asm volatile("s_waitcnt vmcnt(0)" ::: "memory");
;             const unsigned og = xb_add(&bar[XB_TOP], 1u);
;             const unsigned tg = og / nx;
;             if (og + 1u == (tg + 1u) * nx) xb_add(&bar[XB_TOPGEN], 1u);
;             else XB_SPIN(xb_ld(&bar[XB_TOPGEN]) == tg, bar);
;             __builtin_amdgcn_fence(__ATOMIC_ACQUIRE, "agent");
;             xb_add(&bar[XB_XGEN(b.x)], 1u);
;             asm volatile("s_waitcnt vmcnt(0)" ::: "memory");
;         } else {
;             XB_SPIN(xb_ld(&bar[XB_XGEN(b.x)]) == gen, bar);
;             __builtin_amdgcn_fence(__ATOMIC_ACQUIRE, "agent");
;             asm volatile("s_waitcnt vmcnt(0)" ::: "memory");
;         }
;     }
;     __syncthreads();
; }
.Lsm7_done:
.LBB0_1016:
	s_mov_b64 exec, -1
	v_readlane_b32 s8, v252, 17
	v_mov_b32_e32 v9, v222
	v_readlane_b32 s9, v252, 18
	s_waitcnt lgkmcnt(0)
	s_barrier
	s_and_b64 vcc, exec, s[8:9]
	v_readfirstlane_b32 s7, v9
	s_cbranch_vccz .LBB0_1032
	v_lshlrev_b32_e32 v0, 4, v9
	v_add_u32_e32 v1, 0x2000, v0
	v_ashrrev_i32_e32 v2, 31, v1
	v_lshrrev_b32_e32 v2, 22, v2
	v_add_u32_e32 v2, v1, v2
	v_ashrrev_i32_e32 v8, 10, v2
	v_mul_i32_i24_e32 v2, 0x400, v8
	v_sub_u32_e32 v1, v1, v2
	v_lshrrev_b32_e32 v2, 4, v1
	v_bitop3_b32 v1, v2, v1, 32 bitop3:0x6c
	v_ashrrev_i32_e32 v2, 31, v1
	v_lshrrev_b32_e32 v2, 26, v2
	v_add_u32_e32 v2, v1, v2
	v_lshlrev_b32_e32 v3, 3, v8
	v_ashrrev_i32_e32 v10, 6, v2
	v_and_b32_e32 v3, -16, v3
	v_add_u32_e32 v3, v10, v3
	v_and_b32_e32 v4, 3, v10
	s_mov_b32 s6, 0xfffe0
	v_lshrrev_b32_e32 v5, 2, v3
	v_lshlrev_b32_e32 v6, 1, v3
	v_and_b32_e32 v2, 0xc0, v2
	v_and_or_b32 v4, v3, s6, v4
	v_and_b32_e32 v5, 4, v5
	v_and_b32_e32 v6, 24, v6
	v_sub_u32_e32 v1, v1, v2
	v_mov_b32_e32 v2, 1
	v_or3_b32 v4, v4, v5, v6
	v_lshlrev_b32_e32 v5, 5, v8
	v_ashrrev_i16_sdwa v1, v2, sext(v1) dst_sel:DWORD dst_unused:UNUSED_PAD src0_sel:DWORD src1_sel:BYTE_0
	v_and_b32_e32 v5, 32, v5
	v_bfe_i32 v11, v1, 0, 16
	v_add_lshl_u32 v1, v5, v11, 1
	v_lshl_add_u32 v128, v4, 12, v1
	v_lshl_add_u32 v130, v3, 12, v1
	v_bfe_i32 v1, v9, 27, 1
	v_lshrrev_b32_e32 v1, 22, v1
	v_add_u32_e32 v1, v0, v1
	v_and_b32_e32 v1, 0xfffffc00, v1
	v_sub_u32_e32 v0, v0, v1
	v_lshrrev_b32_e32 v1, 4, v0
	v_ashrrev_i32_e32 v3, 31, v9
	v_bitop3_b32 v0, v1, v0, 32 bitop3:0x6c
	v_lshrrev_b32_e32 v3, 26, v3
	v_ashrrev_i32_e32 v1, 31, v0
	v_add_u32_e32 v3, v9, v3
	v_lshrrev_b32_e32 v1, 26, v1
	v_ashrrev_i32_e32 v13, 6, v3
	s_ashr_i32 s10, s7, 6
	v_add_u32_e32 v1, v0, v1
	v_lshlrev_b32_e32 v3, 3, v13
	v_readlane_b32 s8, v252, 29
	s_ashr_i32 s12, s7, 8
	s_lshl_b32 s3, s10, 10
	v_ashrrev_i32_e32 v12, 6, v1
	v_and_b32_e32 v3, -16, v3
	v_readlane_b32 s9, v252, 30
	v_add_u32_e32 v3, v12, v3
	v_and_b32_e32 v4, 3, v12
	s_movk_i32 s14, 0xb1
	s_and_b64 s[8:9], s[8:9], exec
	v_and_or_b32 v4, v3, s6, v4
	s_cselect_b32 s6, s14, 0xb0
	s_mul_i32 s6, s73, s6
	v_readlane_b32 s8, v252, 28
	s_add_i32 s6, s6, s8
	s_mul_hi_i32 s8, s6, 0x2e8ba2e9
	s_lshr_b32 s9, s8, 31
	s_ashr_i32 s8, s8, 6
	s_add_i32 s8, s8, s9
	s_lshl_b32 s9, s8, 3
	s_mulk_i32 s8, 0x160
	s_sub_i32 s8, s6, s8
	s_sext_i32_i16 s6, s8
	s_bfe_u32 s6, s6, 0x3001c
	s_add_i32 s11, s8, s6
	s_sext_i32_i16 s6, s11
	s_and_b32 s11, s11, 0xfff8
	s_sub_i32 s8, s8, s11
	s_sext_i32_i16 s8, s8
	v_lshrrev_b32_e32 v5, 2, v3
	v_lshlrev_b32_e32 v6, 1, v3
	v_and_b32_e32 v1, 0xc0, v1
	s_lshr_b32 s6, s6, 3
	s_add_i32 s26, s9, s8
	v_and_b32_e32 v5, 4, v5
	v_and_b32_e32 v6, 24, v6
	v_sub_u32_e32 v0, v0, v1
	s_ashr_i32 s27, s26, 31
	s_bfe_i64 s[16:17], s[6:7], 0x100000
	v_or3_b32 v4, v4, v5, v6
	v_lshlrev_b32_e32 v5, 5, v13
	v_ashrrev_i16_sdwa v0, v2, sext(v0) dst_sel:DWORD dst_unused:UNUSED_PAD src0_sel:DWORD src1_sel:BYTE_0
	s_lshl_b64 s[8:9], s[26:27], 20
	s_lshl_b64 s[16:17], s[16:17], 20
	v_and_b32_e32 v5, 32, v5
	v_bfe_i32 v14, v0, 0, 16
	s_add_u32 s30, s64, s16
	v_add_lshl_u32 v0, v5, v14, 1
	s_addc_u32 s31, s65, s17
	s_add_i32 s15, s3, 0
	v_lshl_add_u32 v132, v4, 12, v0
	s_add_i32 m0, s15, 0x10000
	v_lshl_add_u32 v134, v3, 12, v0
	global_load_lds_dwordx4 v132, s[30:31]
	s_add_i32 m0, s15, 0x12000
	s_add_u32 s16, s30, 0x80000
	global_load_lds_dwordx4 v128, s[30:31]
	s_addc_u32 s17, s31, 0
	s_add_i32 m0, s15, 0x14000
	v_mov_b32_e32 v133, 0
	global_load_lds_dwordx4 v132, s[16:17]
	s_add_i32 m0, s15, 0x16000
	s_add_u32 s28, s40, s8
	s_addc_u32 s29, s41, s9
	s_add_i32 s22, s15, 0x2000
	global_load_lds_dwordx4 v128, s[16:17]
	s_mov_b32 m0, s15
	s_add_u32 s8, s28, 0x80000
	global_load_lds_dwordx4 v134, s[28:29]
	s_mov_b32 m0, s22
	s_addc_u32 s9, s29, 0
	s_add_i32 s23, s15, 0x4000
	global_load_lds_dwordx4 v130, s[28:29]
	s_mov_b32 m0, s23
	s_add_i32 s27, s15, 0x6000
	global_load_lds_dwordx4 v134, s[8:9]
	s_mov_b32 m0, s27
	v_mov_b32_e32 v129, v133
	global_load_lds_dwordx4 v130, s[8:9]
	v_mov_b32_e32 v135, v133
	v_mov_b32_e32 v131, v133
	s_cmp_eq_u32 s12, 1
	s_mov_b32 s34, 0
	v_lshl_add_u64 v[6:7], s[30:31], 0, v[132:133]
	v_lshl_add_u64 v[4:5], s[30:31], 0, v[128:129]
	v_lshl_add_u64 v[0:1], s[28:29], 0, v[134:135]
	s_cselect_b64 s[8:9], -1, 0
	s_cmp_lg_u32 s12, 1
	v_lshl_add_u64 v[2:3], s[28:29], 0, v[130:131]
	s_cbranch_scc1 .LBB0_1019
	s_barrier

; __device__ __forceinline__ unsigned xb_ld(unsigned* p)              { return __hip_atomic_load(p, __ATOMIC_RELAXED, __HIP_MEMORY_SCOPE_AGENT); }
; __device__ __forceinline__ unsigned xb_add(unsigned* p, unsigned v) { return __hip_atomic_fetch_add(p, v, __ATOMIC_RELAXED, __HIP_MEMORY_SCOPE_AGENT); }
; #define XB_SPIN(cond, bar) do { unsigned _sp = 0; while (cond) { __builtin_amdgcn_s_sleep(1); \
;     if ((++_sp & 255u) == 0u) { if (xb_ld(&(bar)[XB_TMO])) break; if (_sp > XB_SPIN_CAP) { atomicAdd(&(bar)[XB_TMO], 1u); break; } } } } while (0)
; __device__ __forceinline__ void xcd_barrier(const XcdBarrier& b) {
;     asm volatile("s_waitcnt vmcnt(0)" ::: "memory");
;     __syncthreads();
;     if (threadIdx.x == 0) {
;         unsigned* bar = b.bar;
;         __builtin_amdgcn_s_waitcnt(0);
;         unsigned nloc = b.st[0], nx = b.st[1];
;         if (nloc == 0u) { xcd_barrier_complete(bar, b.x, nloc, nx); b.st[0] = nloc; b.st[1] = nx; }
;         const unsigned old = xb_add(&bar[XB_XSUB(b.x)], 1u);
;         const unsigned gen = old / nloc;
;         if (old + 1u == (gen + 1u) * nloc) {
;             __builtin_amdgcn_fence(__ATOMIC_RELEASE, "agent");
;             asm volatile("s_waitcnt vmcnt(0)" ::: "memory");
;             const unsigned og = xb_add(&bar[XB_TOP], 1u);
;             const unsigned tg = og / nx;
;             if (og + 1u == (tg + 1u) * nx) xb_add(&bar[XB_TOPGEN], 1u);
;             else XB_SPIN(xb_ld(&bar[XB_TOPGEN]) == tg, bar);
;             __builtin_amdgcn_fence(__ATOMIC_ACQUIRE, "agent");
;             xb_add(&bar[XB_XGEN(b.x)], 1u);
;             asm volatile("s_waitcnt vmcnt(0)" ::: "memory");
;         } else {
;             XB_SPIN(xb_ld(&bar[XB_XGEN(b.x)]) == gen, bar);
;             __builtin_amdgcn_fence(__ATOMIC_ACQUIRE, "agent");
;             asm volatile("s_waitcnt vmcnt(0)" ::: "memory");
;         }
;     }
;     __syncthreads();
; }
.LBB0_1035:
	s_waitcnt vmcnt(0) lgkmcnt(0)
	s_barrier
	v_readfirstlane_b32 s98, v222
	s_nop 3
	s_cmp_lg_u32 s98, 0
	s_cbranch_scc1 .Lsm8_done
	v_mov_b32_e32 v0, 0x23fc0
	ds_read_b64 v[2:3], v0
	v_readlane_b32 s99, v252, 3
	s_add_u32 s100, s58, 0x507000
	s_addc_u32 s101, s59, 0
	s_lshl_b32 s99, s99, 8
	v_mov_b32_e32 v0, s99
	v_mov_b32_e32 v1, 1
	s_mov_b64 exec, 1
	s_nop 1
	global_atomic_add v4, v0, v1, s[100:101] sc0
	s_waitcnt vmcnt(0) lgkmcnt(0)
	v_readfirstlane_b32 s99, v4
	v_readfirstlane_b32 vcc_lo, v2
	v_readfirstlane_b32 vcc_hi, v3
	s_add_u32 s100, s58, 0x500080
	s_addc_u32 s101, s59, 0
	v_mov_b32_e32 v0, 0
	s_add_u32 s99, s99, 1
	s_mul_i32 s98, vcc_lo, 7
	s_cmp_lg_u32 s99, s98
	s_cbranch_scc1 .Lsm8_nl
	buffer_wbl2 sc1
	s_waitcnt vmcnt(0)
	global_atomic_add v0, v1, s[100:101]
.Lsm8_nl:
	buffer_inv sc1
	s_mul_i32 s98, vcc_hi, 7
	s_mov_b32 s99, 0

; __device__ __forceinline__ unsigned xb_ld(unsigned* p)              { return __hip_atomic_load(p, __ATOMIC_RELAXED, __HIP_MEMORY_SCOPE_AGENT); }
; __device__ __forceinline__ unsigned xb_add(unsigned* p, unsigned v) { return __hip_atomic_fetch_add(p, v, __ATOMIC_RELAXED, __HIP_MEMORY_SCOPE_AGENT); }
; #define XB_SPIN(cond, bar) do { unsigned _sp = 0; while (cond) { __builtin_amdgcn_s_sleep(1); \
;     if ((++_sp & 255u) == 0u) { if (xb_ld(&(bar)[XB_TMO])) break; if (_sp > XB_SPIN_CAP) { atomicAdd(&(bar)[XB_TMO], 1u); break; } } } } while (0)
; __device__ __forceinline__ void xcd_barrier(const XcdBarrier& b) {
;     asm volatile("s_waitcnt vmcnt(0)" ::: "memory");
;     __syncthreads();
;     if (threadIdx.x == 0) {
;         unsigned* bar = b.bar;
;         __builtin_amdgcn_s_waitcnt(0);
;         unsigned nloc = b.st[0], nx = b.st[1];
;         if (nloc == 0u) { xcd_barrier_complete(bar, b.x, nloc, nx); b.st[0] = nloc; b.st[1] = nx; }
;         const unsigned old = xb_add(&bar[XB_XSUB(b.x)], 1u);
;         const unsigned gen = old / nloc;
;         if (old + 1u == (gen + 1u) * nloc) {
;             __builtin_amdgcn_fence(__ATOMIC_RELEASE, "agent");
;             asm volatile("s_waitcnt vmcnt(0)" ::: "memory");
;             const unsigned og = xb_add(&bar[XB_TOP], 1u);
;             const unsigned tg = og / nx;
;             if (og + 1u == (tg + 1u) * nx) xb_add(&bar[XB_TOPGEN], 1u);
;             else XB_SPIN(xb_ld(&bar[XB_TOPGEN]) == tg, bar);
;             __builtin_amdgcn_fence(__ATOMIC_ACQUIRE, "agent");
;             xb_add(&bar[XB_XGEN(b.x)], 1u);
;             asm volatile("s_waitcnt vmcnt(0)" ::: "memory");
;         } else {
;             XB_SPIN(xb_ld(&bar[XB_XGEN(b.x)]) == gen, bar);
;             __builtin_amdgcn_fence(__ATOMIC_ACQUIRE, "agent");
;             asm volatile("s_waitcnt vmcnt(0)" ::: "memory");
;         }
;     }
;     __syncthreads();
; }
; __global__ void __launch_bounds__(512, 2) mega_fwd(Args a) {
;     ...
;     if (G == 256) {
;         Gemm g{ACT, WDN, M_TOK, DMODEL, DFF}; StaticOrder S; S.init(M_TOK, DMODEL, G, (int)blockIdx.x);
;         EpiResNorm E{XR, XR, a.in[17], 0.5f, (float*)(ws + WS_XS), (unsigned*)(ws + WS_BAR) + 4096};
;         gemm_phase<EpiResNorm, StaticOrder, false, true>(lds, g, S, E);
.Lsm8_done:
.LBB0_1088:
	s_mov_b64 exec, -1
	v_readlane_b32 s6, v252, 10
	v_readlane_b32 s7, v252, 11
	s_mov_b64 s[0:1], -1
	s_and_b64 vcc, exec, s[6:7]
	s_waitcnt lgkmcnt(0)
	s_barrier
	s_cbranch_vccz .LBB0_1187
	v_mov_b32_e32 v8, v222
	s_and_b64 vcc, exec, s[4:5]
	v_readfirstlane_b32 s6, v8
	s_cbranch_vccnz .LBB0_1091
	v_readlane_b32 s0, v252, 29
	v_readlane_b32 s1, v252, 30
	s_and_b64 s[0:1], s[0:1], exec
	v_readlane_b32 s0, v252, 31
	v_readlane_b32 s1, v252, 32
	s_cselect_b32 s0, s1, s0
	v_readlane_b32 s1, v252, 28
	s_add_i32 s0, s0, s1
	s_ashr_i32 s1, s0, 31
	s_lshr_b32 s1, s1, 26
	s_add_i32 s1, s0, s1
	s_ashr_i32 s7, s1, 6
	s_andn2_b32 s1, s1, 63
	s_sub_i32 s0, s0, s1
	s_bfe_i32 s1, s0, 0x80000
	s_bfe_u32 s1, s1, 0x3000c
	s_add_i32 s1, s0, s1
	s_bfe_i32 s8, s1, 0x80000
	s_and_b32 s1, s1, 0xf8
	s_sub_i32 s0, s0, s1
	s_lshl_b32 s7, s7, 3
	s_sext_i32_i16 s8, s8
	s_sext_i32_i8 s0, s0
	s_add_i32 s12, s7, s0
	s_ashr_i32 s0, s8, 3

; __global__ void __launch_bounds__(512, 2) mega_fwd(Args a) {
	.amdhsa_kernel _Z8mega_fwd4Args
		.amdhsa_group_segment_fixed_size 0
		.amdhsa_private_segment_fixed_size 0
		.amdhsa_kernarg_size 416
		.amdhsa_user_sgpr_count 2
		.amdhsa_user_sgpr_dispatch_ptr 0
		.amdhsa_user_sgpr_queue_ptr 0
		.amdhsa_user_sgpr_kernarg_segment_ptr 1
		.amdhsa_user_sgpr_dispatch_id 0
		.amdhsa_user_sgpr_kernarg_preload_length 0
		.amdhsa_user_sgpr_kernarg_preload_offset 0
		.amdhsa_user_sgpr_private_segment_size 0
		.amdhsa_uses_dynamic_stack 0
		.amdhsa_enable_private_segment 0
		.amdhsa_system_sgpr_workgroup_id_x 1
		.amdhsa_system_sgpr_workgroup_id_y 0
		.amdhsa_system_sgpr_workgroup_id_z 0
		.amdhsa_system_sgpr_workgroup_info 0
		.amdhsa_system_vgpr_workitem_id 2
		.amdhsa_next_free_vgpr 253
		.amdhsa_next_free_sgpr 102
		.amdhsa_accum_offset 256
		.amdhsa_reserve_vcc 1
		.amdhsa_float_round_mode_32 0
		.amdhsa_float_round_mode_16_64 0
		.amdhsa_float_denorm_mode_32 3
		.amdhsa_float_denorm_mode_16_64 3
		.amdhsa_dx10_clamp 1
		.amdhsa_ieee_mode 1
		.amdhsa_fp16_overflow 0
		.amdhsa_tg_split 0
		.amdhsa_exception_fp_ieee_invalid_op 0
		.amdhsa_exception_fp_denorm_src 0
		.amdhsa_exception_fp_ieee_div_zero 0
		.amdhsa_exception_fp_ieee_overflow 0
		.amdhsa_exception_fp_ieee_underflow 0
		.amdhsa_exception_fp_ieee_inexact 0
		.amdhsa_exception_int_div_zero 0
	.end_amdhsa_kernel

; __global__ void __launch_bounds__(512, 2) mega_fwd(Args a) {
amdhsa.kernels:
  - .agpr_count:     0
    .args:
      - .offset:         0
        .size:           160
        .value_kind:     by_value
      - .offset:         160
        .size:           4
        .value_kind:     hidden_block_count_x
      - .offset:         164
        .size:           4
        .value_kind:     hidden_block_count_y
      - .offset:         168
        .size:           4
        .value_kind:     hidden_block_count_z
      - .offset:         172
        .size:           2
        .value_kind:     hidden_group_size_x
      - .offset:         174
        .size:           2
        .value_kind:     hidden_group_size_y
      - .offset:         176
        .size:           2
        .value_kind:     hidden_group_size_z
      - .offset:         178
        .size:           2
        .value_kind:     hidden_remainder_x
      - .offset:         180
        .size:           2
        .value_kind:     hidden_remainder_y
      - .offset:         182
        .size:           2
        .value_kind:     hidden_remainder_z
      - .offset:         200
        .size:           8
        .value_kind:     hidden_global_offset_x
      - .offset:         208
        .size:           8
        .value_kind:     hidden_global_offset_y
      - .offset:         216
        .size:           8
        .value_kind:     hidden_global_offset_z
      - .offset:         224
        .size:           2
        .value_kind:     hidden_grid_dims
      - .offset:         248
        .size:           8
        .value_kind:     hidden_multigrid_sync_arg
      - .offset:         280
        .size:           4
        .value_kind:     hidden_dynamic_lds_size
    .group_segment_fixed_size: 0
    .kernarg_segment_align: 8
    .kernarg_segment_size: 416
    .language:       OpenCL C
    .language_version:
      - 2
      - 0
    .max_flat_workgroup_size: 512
    .name:           _Z8mega_fwd4Args
    .private_segment_fixed_size: 0
    .sgpr_count:     108
    .sgpr_spill_count: 33
    .symbol:         _Z8mega_fwd4Args.kd
    .uniform_work_group_size: 1
    .uses_dynamic_stack: false
    .vgpr_count:     253
    .vgpr_spill_count: 0
    .wavefront_size: 64
